# v82 plus retention tail statistics via DPP and removal of the now-dead ds_bpermute address computation from the chunk loop
# speedup vs baseline: 1.0039x; 1.0039x over previous
; #define LAS __attribute__((address_space(3)))
; #define LBAR() do { asm volatile("s_waitcnt lgkmcnt(0)" ::: "memory"); __builtin_amdgcn_s_barrier(); asm volatile("" ::: "memory"); } while (0)
; __device__ __forceinline__ unsigned pk2(float lo, float hi) { return pg8::cvt_pk_bf16(lo, hi); }
; __device__ __forceinline__ void retention_unit(LAS unsigned char* lds, const Ptrs& P, int b, int h, int tid) {
;     ...
;     for (int n = 0; n <= 32; ++n) {
;         LAS unsigned char* bufc = lds + (n & 1) * RSET;
;         LAS bf16* Qs = (LAS bf16*)(bufc + ROFF_Q); LAS bf16* Ks = (LAS bf16*)(bufc + ROFF_K); LAS bf16* K2s = (LAS bf16*)(bufc + ROFF_K2); LAS bf16* Vs = (LAS bf16*)(bufc + ROFF_V);
;         if (n < 32) {
;             *(LAS v4u*)(Qs + lrow * S72 + lseg * 8) = rq; *(LAS v4u*)(Ks + lrow * S72 + lseg * 8) = rk;
;             v4u k2;
; #pragma unroll
;             for (int t = 0; t < 4; ++t) k2[t] = pk2(bflo(rk[t]) * dkey, bfhi(rk[t]) * dkey);
;             *(LAS v4u*)(K2s + lrow * S72 + lseg * 8) = k2;
;             *(LAS v4u*)(Vs + vrow0 * S144 + vseg * 8) = rv0; *(LAS v4u*)(Vs + (vrow0 + 32) * S144 + vseg * 8) = rv1;
;         }
;         if (n >= 1) {
; #pragma unroll
;             for (int it = 0; it < 4; ++it) sgr[it] = __builtin_nontemporal_load((const v2u*)(gsl + ((size_t)(n - 1) * 64 + 16 * it) * 512));
;         }
;         LBAR();
;         if (n + 1 < 32) { const size_t o4 = (size_t)(n + 1) * 64;
;             rq = __builtin_nontemporal_load((const v4u*)(gq + o4 * 256)); rk = __builtin_nontemporal_load((const v4u*)(gk + o4 * 256)); rv0 = __builtin_nontemporal_load((const v4u*)(gv + o4 * 512)); rv1 = __builtin_nontemporal_load((const v4u*)(gv + (o4 + 32) * 512)); }
;         if (n >= 1) {
;             const int row = tid >> 3, sub = tid & 7;
;             const f32x4 pa = *(const LAS f32x4*)(part + (row * 32 + sub * 4) * 2), pb = *(const LAS f32x4*)(part + (row * 32 + sub * 4) * 2 + 4);
;             float s1 = (pa[0] + pa[2]) + (pb[0] + pb[2]), s2 = (pa[1] + pa[3]) + (pb[1] + pb[3]);
; #pragma unroll
;             for (int x = 1; x < 8; x <<= 1) { s1 += __shfl_xor(s1, x); s2 += __shfl_xor(s2, x); }
;             if (sub == 0) { const float mean = s1 * (1.f / 128.f); float var = s2 * (1.f / 128.f) - mean * mean; var = var < 0.f ? 0.f : var;
;                 stat[row * 2] = mean; stat[row * 2 + 1] = __builtin_amdgcn_rsqf(var + 1e-5f); }
.LBB0_658:
	s_add_i32 s89, s89, 1
	s_bitcmp1_b32 s89, 0
	s_cselect_b32 s18, 0xb400, 0
	s_add_i32 s90, s18, 0
	v_add3_u32 v52, s90, v163, v72
	s_waitcnt vmcnt(7)
	ds_write_b128 v52, v[36:39]
	s_waitcnt vmcnt(6)
	ds_write_b128 v52, v[24:27] offset:9216
	v_lshlrev_b32_e32 v36, 16, v24
	v_and_b32_e32 v37, 0xffff0000, v24
	v_pk_mul_f32 v[36:37], v[102:103], v[36:37]
	v_add_u32_e32 v56, 0, v159
	v_cvt_pk_bf16_f32 v24, v36, v37
	v_lshlrev_b32_e32 v36, 16, v25
	v_and_b32_e32 v37, 0xffff0000, v25
	v_pk_mul_f32 v[36:37], v[102:103], v[36:37]
	v_add_u32_e32 v139, 0x1d400, v56
	v_cvt_pk_bf16_f32 v25, v36, v37
	v_lshlrev_b32_e32 v36, 16, v26
	v_and_b32_e32 v37, 0xffff0000, v26
	v_pk_mul_f32 v[36:37], v[102:103], v[36:37]
	v_and_b32_e32 v60, 64, v131
	v_cvt_pk_bf16_f32 v26, v36, v37
	v_lshlrev_b32_e32 v36, 16, v27
	v_and_b32_e32 v37, 0xffff0000, v27
	v_pk_mul_f32 v[36:37], v[102:103], v[36:37]
	v_add_u32_e32 v60, 64, v60
	v_cvt_pk_bf16_f32 v27, v36, v37
	ds_write_b128 v52, v[24:27] offset:18432
	v_add3_u32 v24, s90, v158, v84
	s_waitcnt vmcnt(5)
	ds_write_b128 v24, v[28:31] offset:27648
	s_waitcnt vmcnt(4)
	ds_write_b128 v24, v[32:35] offset:36864
	v_lshl_add_u64 v[24:25], s[26:27], 0, v[116:117]
	v_lshl_add_u64 v[24:25], v[24:25], 0, s[12:13]
	v_add_co_u32_e32 v26, vcc, s58, v24
	v_xor_b32_e32 v61, 1, v131
	s_nop 0
	v_addc_co_u32_e32 v27, vcc, 0, v25, vcc
	v_add_co_u32_e32 v28, vcc, s59, v24
	s_nop 1
	v_addc_co_u32_e32 v29, vcc, 0, v25, vcc
	v_add_co_u32_e32 v30, vcc, s60, v24
	s_nop 1
	v_addc_co_u32_e32 v31, vcc, 0, v25, vcc
	v_add_co_u32_e32 v24, vcc, s61, v24
	s_nop 1
	v_addc_co_u32_e32 v25, vcc, 0, v25, vcc
	v_mov_b32_e32 v54, v252
	v_mov_b32_e32 v55, v253
	v_mov_b32_e32 v52, v254
	v_mov_b32_e32 v53, v255
	v_mov_b32_e32 v122, v248
	v_mov_b32_e32 v123, v249
	v_mov_b32_e32 v118, v214
	v_mov_b32_e32 v119, v215
	global_load_dwordx2 v[252:253], v[26:27], off nt
	global_load_dwordx2 v[254:255], v[28:29], off nt
	global_load_dwordx2 v[248:249], v[30:31], off nt
	global_load_dwordx2 v[214:215], v[24:25], off nt
	v_lshl_add_u64 v[24:25], s[26:27], 0, v[110:111]
	v_add_co_u32_e32 v26, vcc, s62, v24
	v_lshl_add_u64 v[28:29], s[26:27], 0, v[112:113]
	s_nop 0
	v_addc_co_u32_e32 v27, vcc, 0, v25, vcc
	v_add_co_u32_e32 v24, vcc, s63, v24
	s_waitcnt lgkmcnt(0)
	s_barrier
	v_lshl_add_u32 v213, v155, 1, s90
	v_add_u32_e32 v75, v213, v62
	v_add_u32_e32 v213, v213, v179
	ds_read_b128 v[216:219], v213 offset:9216
	ds_read_b128 v[220:223], v213 offset:9280
	ds_read_b128 v[188:191], v75
	ds_read_b128 v[192:195], v75 offset:64
	s_nop 0
	v_addc_co_u32_e32 v25, vcc, 0, v25, vcc
	v_add_co_u32_e32 v30, vcc, s64, v28
	global_load_dwordx4 v[36:39], v[26:27], off nt
	s_nop 0
	global_load_dwordx4 v[24:27], v[24:25], off nt
	v_addc_co_u32_e32 v31, vcc, 0, v29, vcc
	v_add_co_u32_e32 v32, vcc, s65, v28
	s_nop 1
	v_addc_co_u32_e32 v33, vcc, 0, v29, vcc
	global_load_dwordx4 v[28:31], v[30:31], off nt
	s_nop 0
	global_load_dwordx4 v[32:35], v[32:33], off nt
	ds_read_b128 v[56:59], v139
	ds_read_b128 v[184:187], v139 offset:16
	s_waitcnt lgkmcnt(1)
	v_pk_add_f32 v[56:57], v[56:57], v[58:59]
	s_waitcnt lgkmcnt(0)
	v_pk_add_f32 v[58:59], v[184:185], v[186:187]
	v_pk_add_f32 v[56:57], v[56:57], v[58:59]
	s_nop 1
	v_add_f32_dpp v56, v56, v56 quad_perm:[1,0,3,2] row_mask:0xf bank_mask:0xf
	v_add_f32_dpp v57, v57, v57 quad_perm:[1,0,3,2] row_mask:0xf bank_mask:0xf
	s_nop 1
	v_add_f32_dpp v56, v56, v56 quad_perm:[2,3,0,1] row_mask:0xf bank_mask:0xf
	v_add_f32_dpp v57, v57, v57 quad_perm:[2,3,0,1] row_mask:0xf bank_mask:0xf
	s_nop 1
	v_add_f32_dpp v56, v56, v56 row_half_mirror row_mask:0xf bank_mask:0xf
	v_add_f32_dpp v57, v57, v57 row_half_mirror row_mask:0xf bank_mask:0xf
	s_and_saveexec_b64 s[18:19], s[0:1]
	s_cbranch_execz .LBB0_657
	s_waitcnt lgkmcnt(0)
	v_add_u32_e32 v58, 0, v198
	v_pk_mul_f32 v[56:57], v[56:57], s[6:7] op_sel_hi:[1,0]
	v_add_u32_e32 v58, 0x21400, v58
	v_fma_f32 v57, -v56, v56, v57
	v_cmp_ngt_f32_e32 vcc, 0, v57
	s_nop 1
	v_cndmask_b32_e32 v57, 0, v57, vcc
	v_add_f32_e32 v57, 0x3727c5ac, v57
	v_rsq_f32_e32 v57, v57
	ds_write2_b32 v58, v56, v57 offset1:1
	s_branch .LBB0_657
.LBB0_660:
	v_mov_b32_e32 v53, s17
	v_or_b32_e32 v52, s16, v144
	v_lshlrev_b64 v[54:55], 10, v[52:53]
	v_lshl_add_u64 v[54:55], s[54:55], 0, v[54:55]
	s_lshl_b32 s4, s4, 1
	v_lshl_add_u64 v[54:55], v[54:55], 0, s[4:5]
	s_lshl_b32 s16, s88, 1
	s_mov_b32 s17, s5
	v_lshl_add_u64 v[54:55], v[54:55], 0, s[16:17]
	v_lshlrev_b32_e32 v62, 1, v146
	v_lshl_add_u64 v[54:55], v[54:55], 0, v[62:63]
	v_add_co_u32_e32 v56, vcc, s70, v54
	s_nop 1
	v_addc_co_u32_e32 v57, vcc, 0, v55, vcc
	v_add_co_u32_e32 v58, vcc, s71, v54
	s_nop 1
	v_addc_co_u32_e32 v59, vcc, 0, v55, vcc
	v_add_co_u32_e32 v112, vcc, s72, v54
	s_nop 1
	v_addc_co_u32_e32 v113, vcc, 0, v55, vcc
	v_add_co_u32_e32 v114, vcc, s73, v54
	s_nop 1
	v_addc_co_u32_e32 v115, vcc, 0, v55, vcc
	global_load_dwordx2 v[110:111], v[56:57], off nt
	global_load_dwordx2 v[60:61], v[58:59], off nt
	s_nop 0
	global_load_dwordx2 v[58:59], v[112:113], off nt
	global_load_dwordx2 v[56:57], v[114:115], off nt
	s_waitcnt vmcnt(11)
	ds_write_b128 v164, v[36:39] offset:46080
	s_waitcnt vmcnt(10)
	ds_write_b128 v164, v[24:27] offset:55296
	v_lshlrev_b32_e32 v36, 16, v24
	v_and_b32_e32 v37, 0xffff0000, v24
	v_pk_mul_f32 v[36:37], v[102:103], v[36:37]
	s_nop 0
	v_cvt_pk_bf16_f32 v24, v36, v37
	v_lshlrev_b32_e32 v36, 16, v25
	v_and_b32_e32 v37, 0xffff0000, v25
	v_pk_mul_f32 v[36:37], v[102:103], v[36:37]
	s_nop 0
	v_cvt_pk_bf16_f32 v25, v36, v37
	v_lshlrev_b32_e32 v36, 16, v26
	v_and_b32_e32 v37, 0xffff0000, v26
	v_pk_mul_f32 v[36:37], v[102:103], v[36:37]
	s_nop 0
	v_cvt_pk_bf16_f32 v26, v36, v37
	v_lshlrev_b32_e32 v36, 16, v27
	v_and_b32_e32 v37, 0xffff0000, v27
	v_pk_mul_f32 v[36:37], v[102:103], v[36:37]
	s_nop 0
	v_cvt_pk_bf16_f32 v27, v36, v37
	ds_write_b128 v164, v[24:27] offset:64512
	s_waitcnt vmcnt(9)
	ds_write_b128 v81, v[28:31]
	s_waitcnt vmcnt(8)
	ds_write_b128 v81, v[32:35] offset:9216
	s_waitcnt lgkmcnt(0)
	s_barrier
; __device__ __forceinline__ void retention_unit(LAS unsigned char* lds, const Ptrs& P, int b, int h, int tid) {
;     ...
;             const int row = tid >> 3, sub = tid & 7;
;             const f32x4 pa = *(const LAS f32x4*)(part + (row * 32 + sub * 4) * 2), pb = *(const LAS f32x4*)(part + (row * 32 + sub * 4) * 2 + 4);
;             float s1 = (pa[0] + pa[2]) + (pb[0] + pb[2]), s2 = (pa[1] + pa[3]) + (pb[1] + pb[3]);
; #pragma unroll
;             for (int x = 1; x < 8; x <<= 1) { s1 += __shfl_xor(s1, x); s2 += __shfl_xor(s2, x); }
;             if (sub == 0) { const float mean = s1 * (1.f / 128.f); float var = s2 * (1.f / 128.f) - mean * mean; var = var < 0.f ? 0.f : var;
;                 stat[row * 2] = mean; stat[row * 2 + 1] = __builtin_amdgcn_rsqf(var + 1e-5f); }
;         }
;         if (n < 32) {
; #pragma unroll
;             for (int j2 = 0; j2 < 2; ++j2) {
;                 const int jt = (w & 1) * 2 + j2; f32x4 a4 = (f32x4){0.f, 0.f, 0.f, 0.f};
; #pragma unroll
;                 for (int ks = 0; ks < 2; ++ks) {
;                     const bf16x8 qf = *(const LAS bf16x8*)(Qs + (16 * it3 + fr) * S72 + 32 * ks + 8 * fq), kf = *(const LAS bf16x8*)(Ks + (16 * jt + fr) * S72 + 32 * ks + 8 * fq);
;                     a4 = mfma16(kf, qf, a4); }
;                 a4 = a4 * decv[j2];
;                 v2u pw; pw.x = pk2(a4[0], a4[1]); pw.y = pk2(a4[2], a4[3]);
;                 *(LAS v2u*)(Ss + (16 * it3 + fr) * S72 + 16 * jt + 4 * fq) = pw;
;             }
;         }
;         LBAR();
;         if (n >= 1) {
; #pragma unroll
;             for (int it = 0; it < 4; ++it) { const int i = 16 * it + fr; const float mean = stat[i * 2], rstd = stat[i * 2 + 1]; const v2u sg = sgr[it];
;                 const f32x4 y = (op[it] - mean) * rstd * gng4 * (f32x4){bflo(sg.x), bfhi(sg.x), bflo(sg.y), bfhi(sg.y)};
;                 v2u pw; pw.x = pk2(y[0], y[1]); pw.y = pk2(y[2], y[3]);
;                 *(v2u*)(gol + ((size_t)(n - 1) * 64 + 16 * it) * 1024) = pw; }
;         }
;         if (n < 32) {
;             f32x4 o[4]; bf16x8 bst[2], bv[2];
; #pragma unroll
;             for (int ks = 0; ks < 2; ++ks) { bst[ks] = *(const LAS bf16x8*)(St + (16 * w + fr) * S72 + 32 * ks + 8 * fq); bv[ks] = tr_frag(bufc + ROFF_V, S144 * 2, w, ks, fq, fr); }
; #pragma unroll
;             for (int it = 0; it < 4; ++it) { o[it] = (f32x4){0.f, 0.f, 0.f, 0.f};
; #pragma unroll
	ds_read_b128 v[24:27], v139
	ds_read_b128 v[28:31], v139 offset:16
	s_waitcnt lgkmcnt(1)
	v_pk_add_f32 v[24:25], v[24:25], v[26:27]
	s_waitcnt lgkmcnt(0)
	v_pk_add_f32 v[26:27], v[28:29], v[30:31]
	v_add_u32_e32 v28, 0, v198
	v_pk_add_f32 v[24:25], v[24:25], v[26:27]
	s_nop 1
	v_add_f32_dpp v24, v24, v24 quad_perm:[1,0,3,2] row_mask:0xf bank_mask:0xf
	v_add_f32_dpp v25, v25, v25 quad_perm:[1,0,3,2] row_mask:0xf bank_mask:0xf
	v_add_u32_e32 v102, 0x21400, v28
	s_nop 1
	v_add_f32_dpp v24, v24, v24 quad_perm:[2,3,0,1] row_mask:0xf bank_mask:0xf
	v_add_f32_dpp v25, v25, v25 quad_perm:[2,3,0,1] row_mask:0xf bank_mask:0xf
	s_nop 1
	v_add_f32_dpp v24, v24, v24 row_half_mirror row_mask:0xf bank_mask:0xf
	v_add_f32_dpp v25, v25, v25 row_half_mirror row_mask:0xf bank_mask:0xf
	s_and_saveexec_b64 s[18:19], s[0:1]
	s_cbranch_execz .LBB0_662
	s_waitcnt lgkmcnt(0)
	s_nop 0
	v_pk_mul_f32 v[24:25], v[24:25], s[6:7] op_sel_hi:[1,0]
	s_nop 0
	v_fma_f32 v25, -v24, v24, v25
	v_cmp_ngt_f32_e32 vcc, 0, v25
	s_nop 1
	v_cndmask_b32_e32 v25, 0, v25, vcc
	v_add_f32_e32 v25, 0x3727c5ac, v25
	v_rsq_f32_e32 v25, v25
	ds_write2_b32 v102, v24, v25 offset1:1
.LBB0_662:
	s_or_b64 exec, exec, s[18:19]
	v_add_u32_e32 v28, v166, v179
	s_waitcnt lgkmcnt(0)
	ds_read_b128 v[24:27], v28 offset:55296
	ds_read_b128 v[28:31], v28 offset:55360
	ds_read_b128 v[32:35], v176 offset:46080
	ds_read_b128 v[36:39], v176 offset:46144
	v_add_u32_e32 v75, v166, v178
	v_lshlrev_b64 v[52:53], 11, v[52:53]
	v_lshl_add_u64 v[52:53], s[44:45], 0, v[52:53]
	s_waitcnt lgkmcnt(1)
	v_mfma_f32_16x16x32_bf16 v[24:27], v[24:27], v[32:35], 0
	v_mul_f32_e64 v16, v76, v16
	v_mul_f32_e64 v17, v77, v17
	v_pk_mul_f32 v[12:13], v[76:77], v[12:13]
	v_pk_mul_f32 v[8:9], v[76:77], v[8:9]
	s_waitcnt lgkmcnt(0)
	v_mfma_f32_16x16x32_bf16 v[24:27], v[28:31], v[36:39], v[24:27]
	v_mul_f32_e64 v4, v76, v4
	v_mul_f32_e64 v5, v77, v5
	s_nop 5
	v_pk_mul_f32 v[26:27], v[100:101], v[26:27]
	v_pk_mul_f32 v[24:25], v[98:99], v[24:25]
	s_waitcnt vmcnt(3)
	v_lshlrev_b32_e32 v98, 16, v110
	v_cvt_pk_bf16_f32 v24, v24, v25
	v_cvt_pk_bf16_f32 v25, v26, v27
	ds_write_b64 v177, v[24:25]
	ds_read_b128 v[24:27], v75 offset:55296
	ds_read_b128 v[28:31], v75 offset:55360
	s_waitcnt lgkmcnt(1)
	v_mfma_f32_16x16x32_bf16 v[24:27], v[24:27], v[32:35], 0
	v_lshl_add_u64 v[32:33], v[52:53], 0, s[4:5]
	v_lshl_add_u64 v[32:33], v[32:33], 0, s[16:17]
	v_lshl_add_u64 v[52:53], v[32:33], 0, v[62:63]
	s_waitcnt lgkmcnt(0)
	v_mfma_f32_16x16x32_bf16 v[24:27], v[28:31], v[36:39], v[24:27]
	v_and_b32_e32 v99, 0xffff0000, v110
	v_lshlrev_b32_e32 v100, 16, v111
	v_and_b32_e32 v101, 0xffff0000, v111
	v_add_co_u32_e32 v28, vcc, s74, v52
	v_add3_u32 v36, v83, s87, v168
	s_nop 2
	v_pk_mul_f32 v[26:27], v[94:95], v[26:27]
	v_pk_mul_f32 v[24:25], v[92:93], v[24:25]
	v_addc_co_u32_e32 v29, vcc, 0, v53, vcc
	v_cvt_pk_bf16_f32 v24, v24, v25
	v_cvt_pk_bf16_f32 v25, v26, v27
	ds_write_b64 v142, v[24:25]
	s_waitcnt lgkmcnt(0)
	s_barrier
	ds_read2_b64 v[24:27], v143 offset1:16
	v_add_u32_e32 v62, v167, v171
	s_waitcnt vmcnt(1)
	v_lshlrev_b32_e32 v94, 16, v58
	v_and_b32_e32 v95, 0xffff0000, v58
	v_lshlrev_b32_e32 v58, 16, v59
	s_waitcnt lgkmcnt(0)
	v_sub_f32_e32 v31, v41, v24
	v_sub_f32_e32 v30, v40, v24
	v_sub_f32_e32 v33, v43, v24
	v_sub_f32_e32 v32, v42, v24
	v_pk_mul_f32 v[32:33], v[24:25], v[32:33] op_sel:[1,0]
	v_pk_mul_f32 v[24:25], v[24:25], v[30:31] op_sel:[1,0]
	v_pk_mul_f32 v[30:31], v[2:3], v[32:33]
	v_pk_mul_f32 v[24:25], v[0:1], v[24:25]
	v_pk_mul_f32 v[30:31], v[30:31], v[100:101]
	v_pk_mul_f32 v[24:25], v[24:25], v[98:99]
	v_sub_f32_e32 v35, v45, v26
	v_cvt_pk_bf16_f32 v24, v24, v25
	v_cvt_pk_bf16_f32 v25, v30, v31
	global_store_dwordx2 v[28:29], v[24:25], off
	v_sub_f32_e32 v25, v47, v26
	v_sub_f32_e32 v24, v46, v26
	v_pk_mul_f32 v[24:25], v[26:27], v[24:25] op_sel:[1,0]
	v_sub_f32_e32 v34, v44, v26
	v_pk_mul_f32 v[24:25], v[2:3], v[24:25]
	v_lshlrev_b32_e32 v30, 16, v61
	v_and_b32_e32 v31, 0xffff0000, v61
	v_pk_mul_f32 v[26:27], v[26:27], v[34:35] op_sel:[1,0]
	v_pk_mul_f32 v[24:25], v[24:25], v[30:31]
	ds_read2_b64 v[30:33], v143 offset0:32 offset1:48
	v_pk_mul_f32 v[26:27], v[0:1], v[26:27]
	v_lshlrev_b32_e32 v28, 16, v60
	v_and_b32_e32 v29, 0xffff0000, v60
	v_pk_mul_f32 v[26:27], v[26:27], v[28:29]
	ds_read_b128 v[42:45], v137
	v_cvt_pk_bf16_f32 v26, v26, v27
	v_cvt_pk_bf16_f32 v27, v24, v25
	v_add_co_u32_e32 v24, vcc, s75, v52
	v_and_b32_e32 v59, 0xffff0000, v59
	s_nop 0
	v_addc_co_u32_e32 v25, vcc, 0, v53, vcc
	global_store_dwordx2 v[24:25], v[26:27], off
	s_waitcnt lgkmcnt(1)
	v_sub_f32_e32 v25, v49, v30
	v_sub_f32_e32 v24, v48, v30
	v_sub_f32_e32 v27, v51, v30
	v_sub_f32_e32 v26, v50, v30
	v_pk_mul_f32 v[26:27], v[30:31], v[26:27] op_sel:[1,0]
	v_pk_mul_f32 v[24:25], v[30:31], v[24:25] op_sel:[1,0]
	v_pk_mul_f32 v[60:61], v[2:3], v[26:27]
	v_pk_mul_f32 v[50:51], v[0:1], v[24:25]
	ds_read_b128 v[24:27], v128 offset:46080
	ds_read_b128 v[46:49], v137 offset:64
	ds_read_b128 v[28:31], v128 offset:46144
	s_waitcnt lgkmcnt(2)
	v_mfma_f32_16x16x32_bf16 v[24:27], v[42:45], v[24:27], 0
	ds_read_b64_tr_b16 v[38:39], v36
	ds_read_b64_tr_b16 v[40:41], v36 offset:1152
	ds_read_b64_tr_b16 v[34:35], v36 offset:9216
	ds_read_b64_tr_b16 v[36:37], v36 offset:10368
	v_pk_mul_f32 v[50:51], v[50:51], v[94:95]
	v_mov_b32_e32 v75, v74
	s_waitcnt lgkmcnt(4)
	v_mfma_f32_16x16x32_bf16 v[24:27], v[46:49], v[28:31], v[24:27]
	ds_read_b128 v[28:31], v129
	v_cvt_pk_bf16_f32 v50, v50, v51
	v_pk_mul_f32 v[18:19], v[74:75], v[18:19]
	v_pk_mul_f32 v[14:15], v[74:75], v[14:15]
	v_pk_mul_f32 v[10:11], v[74:75], v[10:11]
	s_nop 2
	v_pk_mul_f32 v[26:27], v[108:109], v[26:27]
	v_pk_mul_f32 v[24:25], v[90:91], v[24:25]
	ds_read_b128 v[90:93], v129 offset:64
	ds_read_b64_tr_b16 v[98:99], v130 offset:64512
	ds_read_b64_tr_b16 v[100:101], v130 offset:65088
	s_waitcnt lgkmcnt(3)
; #define LAS __attribute__((address_space(3)))
; __device__ __forceinline__ unsigned pk2(float lo, float hi) { return pg8::cvt_pk_bf16(lo, hi); }
; __device__ __forceinline__ void retention_unit(LAS unsigned char* lds, const Ptrs& P, int b, int h, int tid) {
;     ...
;         if (n >= 1) {
; #pragma unroll
;             for (int it = 0; it < 4; ++it) { const int i = 16 * it + fr; const float mean = stat[i * 2], rstd = stat[i * 2 + 1]; const v2u sg = sgr[it];
;                 const f32x4 y = (op[it] - mean) * rstd * gng4 * (f32x4){bflo(sg.x), bfhi(sg.x), bflo(sg.y), bfhi(sg.y)};
;                 v2u pw; pw.x = pk2(y[0], y[1]); pw.y = pk2(y[2], y[3]);
;                 *(v2u*)(gol + ((size_t)(n - 1) * 64 + 16 * it) * 1024) = pw; }
;         }
;         if (n < 32) {
;             f32x4 o[4]; bf16x8 bst[2], bv[2];
; #pragma unroll
;             for (int ks = 0; ks < 2; ++ks) { bst[ks] = *(const LAS bf16x8*)(St + (16 * w + fr) * S72 + 32 * ks + 8 * fq); bv[ks] = tr_frag(bufc + ROFF_V, S144 * 2, w, ks, fq, fr); }
; #pragma unroll
;             for (int it = 0; it < 4; ++it) { o[it] = (f32x4){0.f, 0.f, 0.f, 0.f};
; #pragma unroll
;                 for (int ks = 0; ks < 2; ++ks) { const bf16x8 qf = *(const LAS bf16x8*)(Qs + (16 * it + fr) * S72 + 32 * ks + 8 * fq); o[it] = mfma16(bst[ks], qf, o[it]); }
;                 o[it] = o[it] * dqv[it];
; #pragma unroll
;                 for (int ks = 0; ks < 2; ++ks) { const bf16x8 sf = *(const LAS bf16x8*)(Ss + (16 * it + fr) * S72 + 32 * ks + 8 * fq); o[it] = mfma16(bv[ks], sf, o[it]); }
;             }
; #pragma unroll
;             for (int dt = 0; dt < 4; ++dt) { st[dt] = st[dt] * dch;
; #pragma unroll
;                 for (int ks = 0; ks < 2; ++ks) { const bf16x8 kf = tr_frag(bufc + ROFF_K2, S72 * 2, dt, ks, fq, fr); st[dt] = mfma16(kf, bv[ks], st[dt]); }
;                 v2u pw; pw.x = pk2(st[dt][0], st[dt][1]); pw.y = pk2(st[dt][2], st[dt][3]);
;                 *(LAS v2u*)(St + (16 * w + fr) * S72 + 16 * dt + 4 * fq) = pw; }
; #pragma unroll
;             for (int it = 0; it < 4; ++it) { const f32x4 v = o[it]; typedef float f32x2 __attribute__((ext_vector_type(2)));
;                 *(LAS f32x2*)(part + ((16 * it + fr) * 32 + w * 4 + fq) * 2) = (f32x2){(v[0] + v[1]) + (v[2] + v[3]), (v[0] * v[0] + v[1] * v[1]) + (v[2] * v[2] + v[3] * v[3])};
;                 op[it] = v; }
	v_mfma_f32_16x16x32_bf16 v[24:27], v[38:41], v[28:31], v[24:27]
	ds_read_b128 v[108:111], v128 offset:48384
	ds_read_b64_tr_b16 v[112:113], v62 offset:64512
	ds_read_b64_tr_b16 v[114:115], v62 offset:65088
	v_pk_mul_f32 v[6:7], v[74:75], v[6:7]
	s_waitcnt lgkmcnt(5)
	v_mfma_f32_16x16x32_bf16 v[28:31], v[34:37], v[90:93], v[24:27]
	s_nop 2
	ds_read_b128 v[24:27], v128 offset:48448
	s_waitcnt lgkmcnt(3)
	v_mfma_f32_16x16x32_bf16 v[90:93], v[42:45], v[108:111], 0
	v_mul_f32_e64 v108, v60, v58
	v_mul_f32_e64 v109, v61, v59
	ds_read_b128 v[58:61], v129 offset:2304
	v_cvt_pk_bf16_f32 v51, v108, v109
	s_waitcnt lgkmcnt(1)
	v_mfma_f32_16x16x32_bf16 v[24:27], v[46:49], v[24:27], v[90:93]
	v_mfma_f32_16x16x32_bf16 v[16:19], v[98:101], v[38:41], v[16:19]
	s_nop 1
	ds_read_b128 v[90:93], v129 offset:2368
	s_nop 3
	v_pk_mul_f32 v[26:27], v[106:107], v[26:27]
	v_pk_mul_f32 v[24:25], v[78:79], v[24:25]
	ds_read_b128 v[106:109], v129 offset:4608
	v_mfma_f32_16x16x32_bf16 v[16:19], v[112:115], v[34:37], v[16:19]
	v_add_co_u32_e32 v78, vcc, s76, v52
	s_waitcnt lgkmcnt(2)
	v_mfma_f32_16x16x32_bf16 v[24:27], v[38:41], v[58:61], v[24:27]
	ds_read_b128 v[58:61], v128 offset:50688
	v_addc_co_u32_e32 v79, vcc, 0, v53, vcc
	s_waitcnt lgkmcnt(2)
	v_mfma_f32_16x16x32_bf16 v[24:27], v[34:37], v[90:93], v[24:27]
	ds_read_b128 v[90:93], v128 offset:50752
	global_store_dwordx2 v[78:79], v[50:51], off
	v_cvt_pk_bf16_f32 v16, v16, v17
	s_waitcnt lgkmcnt(1)
	v_mfma_f32_16x16x32_bf16 v[58:61], v[42:45], v[58:61], 0
	v_cvt_pk_bf16_f32 v17, v18, v19
	v_sub_f32_e32 v51, v21, v32
	v_sub_f32_e32 v50, v20, v32
	s_waitcnt lgkmcnt(0)
	v_mfma_f32_16x16x32_bf16 v[58:61], v[46:49], v[90:93], v[58:61]
	ds_read_b128 v[90:93], v129 offset:4672
	v_sub_f32_e32 v79, v23, v32
	v_sub_f32_e32 v78, v22, v32
	v_pk_mul_f32 v[78:79], v[32:33], v[78:79] op_sel:[1,0]
	v_pk_mul_f32 v[32:33], v[32:33], v[50:51] op_sel:[1,0]
	s_nop 2
	v_pk_mul_f32 v[60:61], v[104:105], v[60:61]
	v_pk_mul_f32 v[58:59], v[86:87], v[58:59]
	v_pk_mul_f32 v[32:33], v[0:1], v[32:33]
	s_nop 0
	v_mfma_f32_16x16x32_bf16 v[58:61], v[38:41], v[106:109], v[58:61]
	s_waitcnt lgkmcnt(0)
	v_mfma_f32_16x16x32_bf16 v[20:23], v[34:37], v[90:93], v[58:61]
	s_nop 5
	ds_read_b128 v[58:61], v128 offset:52992
	ds_read_b128 v[90:93], v128 offset:53056
	ds_read_b128 v[98:101], v129 offset:6912
	ds_read_b128 v[104:107], v129 offset:6976
	ds_write_b64 v132, v[16:17]
	ds_read_b64_tr_b16 v[16:17], v130 offset:64544
	ds_read_b64_tr_b16 v[18:19], v130 offset:65120
	s_waitcnt lgkmcnt(6)
	v_mfma_f32_16x16x32_bf16 v[42:45], v[42:45], v[58:61], 0
	ds_read_b64_tr_b16 v[58:59], v62 offset:64544
	ds_read_b64_tr_b16 v[60:61], v62 offset:65120
	s_waitcnt lgkmcnt(2)
	v_mfma_f32_16x16x32_bf16 v[12:15], v[16:19], v[38:41], v[12:15]
	s_waitcnt lgkmcnt(0)
	v_mfma_f32_16x16x32_bf16 v[12:15], v[58:61], v[34:37], v[12:15]
	v_mfma_f32_16x16x32_bf16 v[42:45], v[46:49], v[90:93], v[42:45]
	v_mul_f32_e64 v46, v2, v78
	v_mul_f32_e64 v47, v3, v79
	s_nop 4
	v_cvt_pk_bf16_f32 v12, v12, v13
	v_cvt_pk_bf16_f32 v13, v14, v15
	ds_write_b64 v132, v[12:13] offset:32
	ds_read_b64_tr_b16 v[12:13], v130 offset:64576
	ds_read_b64_tr_b16 v[14:15], v130 offset:65152
	v_pk_mul_f32 v[18:19], v[96:97], v[44:45]
	v_pk_mul_f32 v[16:17], v[88:89], v[42:43]
	ds_read_b64_tr_b16 v[42:43], v62 offset:64576
	ds_read_b64_tr_b16 v[44:45], v62 offset:65152
	s_waitcnt lgkmcnt(2)
	v_mfma_f32_16x16x32_bf16 v[8:11], v[12:15], v[38:41], v[8:11]
	s_waitcnt vmcnt(3)
	v_lshlrev_b32_e32 v12, 16, v57
	v_and_b32_e32 v13, 0xffff0000, v57
	v_pk_mul_f32 v[46:47], v[46:47], v[12:13]
	s_waitcnt lgkmcnt(0)
	v_mfma_f32_16x16x32_bf16 v[8:11], v[42:45], v[34:37], v[8:11]
	v_lshlrev_b32_e32 v48, 16, v56
	v_and_b32_e32 v49, 0xffff0000, v56
	v_mfma_f32_16x16x32_bf16 v[16:19], v[38:41], v[98:101], v[16:19]
	s_nop 4
	v_cvt_pk_bf16_f32 v8, v8, v9
	v_cvt_pk_bf16_f32 v9, v10, v11
	ds_write_b64 v132, v[8:9] offset:64
	ds_read_b64_tr_b16 v[12:13], v130 offset:64608
	ds_read_b64_tr_b16 v[14:15], v130 offset:65184
	v_pk_mul_f32 v[8:9], v[32:33], v[48:49]
	s_waitcnt lgkmcnt(0)
	v_mfma_f32_16x16x32_bf16 v[4:7], v[12:15], v[38:41], v[4:7]
	v_cvt_pk_bf16_f32 v32, v8, v9
	v_add_co_u32_e32 v12, vcc, s77, v52
	v_mfma_f32_16x16x32_bf16 v[8:11], v[34:37], v[104:107], v[16:19]
	s_nop 2
	ds_read_b64_tr_b16 v[16:17], v62 offset:64608
	ds_read_b64_tr_b16 v[18:19], v62 offset:65184
	v_addc_co_u32_e32 v13, vcc, 0, v53, vcc
	s_waitcnt lgkmcnt(0)
	v_mfma_f32_16x16x32_bf16 v[4:7], v[16:19], v[34:37], v[4:7]
	v_cvt_pk_bf16_f32 v33, v46, v47
	global_store_dwordx2 v[12:13], v[32:33], off
	v_mul_f32_e32 v33, v30, v30
	s_nop 4
	v_cvt_pk_bf16_f32 v4, v4, v5
	v_cvt_pk_bf16_f32 v5, v6, v7
	ds_write_b64 v132, v[4:5] offset:96
	v_add_co_u32_e32 v4, vcc, s78, v54
	v_mul_f32_e32 v35, v31, v31
	s_nop 0
	v_addc_co_u32_e32 v5, vcc, 0, v55, vcc
	v_add_co_u32_e32 v6, vcc, s79, v54
	v_mov_b32_e32 v32, v30
	s_nop 0
	v_addc_co_u32_e32 v7, vcc, 0, v55, vcc
	v_add_co_u32_e32 v16, vcc, s80, v54
	v_mov_b32_e32 v34, v31
	s_nop 0
	v_addc_co_u32_e32 v17, vcc, 0, v55, vcc
	v_add_co_u32_e32 v18, vcc, s81, v54
	s_nop 1
	v_addc_co_u32_e32 v19, vcc, 0, v55, vcc
	global_load_dwordx2 v[14:15], v[4:5], off nt
	global_load_dwordx2 v[12:13], v[6:7], off nt
	s_nop 0
	global_load_dwordx2 v[6:7], v[16:17], off nt
	global_load_dwordx2 v[4:5], v[18:19], off nt
	v_mul_f32_e32 v17, v28, v28
	v_mul_f32_e32 v19, v29, v29
	v_mov_b32_e32 v16, v28
	v_mov_b32_e32 v18, v29
	v_pk_add_f32 v[16:17], v[16:17], v[18:19]
	v_pk_add_f32 v[18:19], v[32:33], v[34:35]
	v_mul_f32_e32 v33, v26, v26
	v_pk_add_f32 v[16:17], v[16:17], v[18:19]
	ds_write_b64 v133, v[16:17]
	v_mul_f32_e32 v17, v24, v24
	v_mul_f32_e32 v19, v25, v25
	v_mul_f32_e32 v35, v27, v27
	v_mov_b32_e32 v16, v24
	v_mov_b32_e32 v18, v25
	v_mov_b32_e32 v32, v26
	v_mov_b32_e32 v34, v27
	v_pk_add_f32 v[16:17], v[16:17], v[18:19]
	v_pk_add_f32 v[18:19], v[32:33], v[34:35]
	v_mul_f32_e32 v33, v22, v22
	v_pk_add_f32 v[16:17], v[16:17], v[18:19]
	ds_write_b64 v134, v[16:17]
	v_mul_f32_e32 v17, v20, v20
	v_mul_f32_e32 v19, v21, v21
	v_mul_f32_e32 v35, v23, v23
	v_mov_b32_e32 v16, v20
	v_mov_b32_e32 v18, v21
	v_mov_b32_e32 v32, v22
	v_mov_b32_e32 v34, v23
	v_pk_add_f32 v[16:17], v[16:17], v[18:19]
	v_pk_add_f32 v[18:19], v[32:33], v[34:35]
	v_mul_f32_e32 v33, v10, v10
	v_pk_add_f32 v[16:17], v[16:17], v[18:19]
	ds_write_b64 v135, v[16:17]
	v_mul_f32_e32 v17, v8, v8
	v_mul_f32_e32 v19, v9, v9
	v_mul_f32_e32 v35, v11, v11
	v_mov_b32_e32 v16, v8
	v_mov_b32_e32 v18, v9
	v_mov_b32_e32 v32, v10
	v_mov_b32_e32 v34, v11
	v_pk_add_f32 v[16:17], v[16:17], v[18:19]
	v_pk_add_f32 v[18:19], v[32:33], v[34:35]
	s_nop 0
	v_pk_add_f32 v[16:17], v[16:17], v[18:19]
	ds_write_b64 v136, v[16:17]
	s_waitcnt lgkmcnt(0)
	s_barrier
; #define LAS __attribute__((address_space(3)))
; __device__ __forceinline__ void retention_unit(LAS unsigned char* lds, const Ptrs& P, int b, int h, int tid) {
;     ...
;             const int row = tid >> 3, sub = tid & 7;
;             const f32x4 pa = *(const LAS f32x4*)(part + (row * 32 + sub * 4) * 2), pb = *(const LAS f32x4*)(part + (row * 32 + sub * 4) * 2 + 4);
;             float s1 = (pa[0] + pa[2]) + (pb[0] + pb[2]), s2 = (pa[1] + pa[3]) + (pb[1] + pb[3]);
; #pragma unroll
;             for (int x = 1; x < 8; x <<= 1) { s1 += __shfl_xor(s1, x); s2 += __shfl_xor(s2, x); }
;             if (sub == 0) { const float mean = s1 * (1.f / 128.f); float var = s2 * (1.f / 128.f) - mean * mean; var = var < 0.f ? 0.f : var;
;                 stat[row * 2] = mean; stat[row * 2 + 1] = __builtin_amdgcn_rsqf(var + 1e-5f); }
	ds_read_b128 v[16:19], v139
	ds_read_b128 v[32:35], v139 offset:16
	s_waitcnt lgkmcnt(1)
	v_pk_add_f32 v[16:17], v[16:17], v[18:19]
	s_waitcnt lgkmcnt(0)
	v_pk_add_f32 v[18:19], v[32:33], v[34:35]
	s_nop 0
	v_pk_add_f32 v[16:17], v[16:17], v[18:19]
	s_nop 1
	v_add_f32_dpp v16, v16, v16 quad_perm:[1,0,3,2] row_mask:0xf bank_mask:0xf
	v_add_f32_dpp v17, v17, v17 quad_perm:[1,0,3,2] row_mask:0xf bank_mask:0xf
	s_nop 1
	v_add_f32_dpp v16, v16, v16 quad_perm:[2,3,0,1] row_mask:0xf bank_mask:0xf
	v_add_f32_dpp v17, v17, v17 quad_perm:[2,3,0,1] row_mask:0xf bank_mask:0xf
	s_nop 1
	v_add_f32_dpp v16, v16, v16 row_half_mirror row_mask:0xf bank_mask:0xf
	v_add_f32_dpp v17, v17, v17 row_half_mirror row_mask:0xf bank_mask:0xf
	s_and_saveexec_b64 s[16:17], s[0:1]
	s_cbranch_execz .LBB0_653
	s_waitcnt lgkmcnt(0)
	s_nop 0
	v_pk_mul_f32 v[16:17], v[16:17], s[6:7] op_sel_hi:[1,0]
	s_nop 0
	v_fma_f32 v17, -v16, v16, v17
	v_cmp_ngt_f32_e32 vcc, 0, v17
	s_nop 1
	v_cndmask_b32_e32 v17, 0, v17, vcc
	v_add_f32_e32 v17, 0x3727c5ac, v17
	v_rsq_f32_e32 v17, v17
	ds_write2_b32 v102, v16, v17 offset1:1
	s_branch .LBB0_653
